# P4 w_o residual epilogue: f32/bf16 residual rows fetched ahead (16 loads in flight), counted vmcnt; on top of P7+P3 epilogues
# speedup vs baseline: 1.0272x; 1.0124x over previous
; #define PG8_STAGE(bufoff, gbase, voff) do { _Pragma("unroll") for (int _i = 0; _i < 2; ++_i) \
;         __builtin_amdgcn_global_load_lds((const unsigned*)((const char*)(gbase) + (voff)[_i]), (PG8_LAS unsigned*)(lds + (bufoff) + ldsw + _i * 8192), 16, 0, 0); } while (0)
; #define PG8_LDA(dst, b, h) do { _Pragma("unroll") for (int m = 0; m < 4; ++m) _Pragma("unroll") for (int k = 0; k < 2; ++k) dst[m][k] = *(const PG8_LAS bf16x8*)(lds + PG8_SA(b, h) + aoff + m * 2048 + k * 1024); } while (0)
; #define PG8_LDB(dst, b, h) do { _Pragma("unroll") for (int n = 0; n < 2; ++n) _Pragma("unroll") for (int k = 0; k < 2; ++k) dst[n][k] = *(const PG8_LAS bf16x8*)(lds + PG8_SB(b, h) + boff + n * 2048 + k * 1024); } while (0)
; #define PG8_MMA(ai, bj, At, Bt) do { __builtin_amdgcn_s_setprio(1); _Pragma("unroll") for (int m = 0; m < 4; ++m) _Pragma("unroll") for (int n = 0; n < 2; ++n) _Pragma("unroll") for (int k = 0; k < 2; ++k) \
;         acc[ai][bj][m][n] = __builtin_amdgcn_mfma_f32_16x16x32_bf16(Bt[n][k], At[m][k], acc[ai][bj][m][n], 0, 0, 0); __builtin_amdgcn_s_setprio(0); } while (0)
; #define PG8_WAIT_V(n) asm volatile("s_waitcnt vmcnt(" #n ")" ::: "memory")
; #define PG8_BAR __builtin_amdgcn_s_barrier()
; template <class Epi, class Sched, bool ALIGN_EPI = false, bool SP2 = false>
; __device__ __forceinline__ void gemm_phase(PG8_LAS unsigned char* lds, const Gemm g, const Sched& S, const Epi& E) {
;     ...
;         for (int t = 0; t < nt; t += 2) {
;             const bool last = (t == nt - 2);
;             const char* a1 = cA + (size_t)(t + 1) * kstep;
;             const char* a2 = last ? nA : cA + (size_t)(t + 2) * kstep; const char* b2 = last ? nB : cB + (size_t)(t + 2) * kstep;
;             const char* a3 = a2 + kstep; const char* b3 = b2 + kstep;
;             if (last && has_next) S.a_ready(nxt);
;             if constexpr (SP2) {
;             PG8_LDB(B0, 0, 0); PG8_LDB(B1, 0, 1); PG8_SCHED; PG8_LDA(At, 0, 0); PG8_STAGE(PG8_SA(1, 1), a1 + hstep, voffA);
;             PG8_WAIT_V(8); PG8_WAIT_L(0); PG8_BAR; PG8_MMA(0, 0, At, B0); PG8_MMA(0, 1, At, B1); PG8_BAR; PG8_SCHED;
;             PG8_LDA(At, 0, 1); PG8_STAGE(PG8_SB(0, 0), b2, voffB); PG8_STAGE(PG8_SB(0, 1), b2 + hstep, voffB); PG8_STAGE(PG8_SA(0, 0), a2, voffA);
;             PG8_WAIT_V(8); PG8_WAIT_L(0); PG8_BAR; PG8_MMA(1, 0, At, B0); PG8_MMA(1, 1, At, B1); PG8_BAR; PG8_SCHED;
.LBB0_874:
	s_add_u32 s28, s26, 0xfffc0080
	s_addc_u32 s29, s27, -1
	s_add_i32 s51, 0, 0x10000
	s_cmp_eq_u32 s9, s1
	s_cselect_b32 s31, s17, s29
	s_cselect_b32 s30, s47, s28
	v_add_u32_e32 v150, s51, v154
	s_cselect_b32 s29, s19, s50
	s_cselect_b32 s28, s48, s49
	s_add_i32 s54, 0, 0x14000
	ds_read_b128 v[128:131], v150
	ds_read_b128 v[132:135], v150 offset:1024
	ds_read_b128 v[146:149], v150 offset:2048
	ds_read_b128 v[158:161], v150 offset:3072
	v_add_u32_e32 v150, s54, v154
	ds_read_b128 v[162:165], v150
	ds_read_b128 v[166:169], v150 offset:1024
	ds_read_b128 v[170:173], v150 offset:2048
	ds_read_b128 v[174:177], v150 offset:3072
	v_lshl_add_u64 v[150:151], s[26:27], 0, v[142:143]
	s_add_i32 m0, s38, 0xc000
	ds_read_b128 v[178:181], v156
	ds_read_b128 v[182:185], v156 offset:1024
	ds_read_b128 v[194:197], v156 offset:2048
	ds_read_b128 v[198:201], v156 offset:3072
	ds_read_b128 v[202:205], v156 offset:4096
	ds_read_b128 v[210:213], v156 offset:5120
	ds_read_b128 v[214:217], v156 offset:6144
	ds_read_b128 v[218:221], v156 offset:7168
	global_load_lds_dwordx4 v[150:151], off
	v_lshl_add_u64 v[150:151], s[26:27], 0, v[144:145]
	s_add_i32 m0, s38, 0xe000
	s_nop 0
	global_load_lds_dwordx4 v[150:151], off
	s_waitcnt vmcnt(8)
	s_waitcnt lgkmcnt(0)
	s_barrier
	s_setprio 1
	s_waitcnt lgkmcnt(0)
	v_mfma_f32_16x16x32_bf16 v[124:127], v[128:131], v[178:181], v[124:127]
	v_mfma_f32_16x16x32_bf16 v[120:123], v[146:149], v[178:181], v[120:123]
	v_mfma_f32_16x16x32_bf16 v[108:111], v[128:131], v[194:197], v[108:111]
	v_mfma_f32_16x16x32_bf16 v[104:107], v[146:149], v[194:197], v[104:107]
	v_mfma_f32_16x16x32_bf16 v[92:95], v[128:131], v[202:205], v[92:95]
	v_mfma_f32_16x16x32_bf16 v[88:91], v[146:149], v[202:205], v[88:91]
	v_mfma_f32_16x16x32_bf16 v[76:79], v[128:131], v[214:217], v[76:79]
	v_mfma_f32_16x16x32_bf16 v[72:75], v[146:149], v[214:217], v[72:75]
	v_mfma_f32_16x16x32_bf16 v[124:127], v[132:135], v[182:185], v[124:127]
	v_mfma_f32_16x16x32_bf16 v[120:123], v[158:161], v[182:185], v[120:123]
	v_mfma_f32_16x16x32_bf16 v[108:111], v[132:135], v[198:201], v[108:111]
	v_mfma_f32_16x16x32_bf16 v[104:107], v[158:161], v[198:201], v[104:107]
	v_mfma_f32_16x16x32_bf16 v[92:95], v[132:135], v[210:213], v[92:95]
	v_mfma_f32_16x16x32_bf16 v[88:91], v[158:161], v[210:213], v[88:91]
	v_mfma_f32_16x16x32_bf16 v[76:79], v[132:135], v[218:221], v[76:79]
	v_mfma_f32_16x16x32_bf16 v[72:75], v[158:161], v[218:221], v[72:75]
	s_setprio 0
	s_setprio 1
	v_mfma_f32_16x16x32_bf16 v[116:119], v[162:165], v[178:181], v[116:119]
	v_mfma_f32_16x16x32_bf16 v[112:115], v[170:173], v[178:181], v[112:115]
	v_mfma_f32_16x16x32_bf16 v[100:103], v[162:165], v[194:197], v[100:103]
	v_mfma_f32_16x16x32_bf16 v[96:99], v[170:173], v[194:197], v[96:99]
	v_mfma_f32_16x16x32_bf16 v[84:87], v[162:165], v[202:205], v[84:87]
	v_mfma_f32_16x16x32_bf16 v[80:83], v[170:173], v[202:205], v[80:83]
	v_mfma_f32_16x16x32_bf16 v[68:71], v[162:165], v[214:217], v[68:71]
	v_mfma_f32_16x16x32_bf16 v[64:67], v[170:173], v[214:217], v[64:67]
	v_mfma_f32_16x16x32_bf16 v[116:119], v[166:169], v[182:185], v[116:119]
	v_mfma_f32_16x16x32_bf16 v[112:115], v[174:177], v[182:185], v[112:115]
	v_mfma_f32_16x16x32_bf16 v[100:103], v[166:169], v[198:201], v[100:103]
	v_mfma_f32_16x16x32_bf16 v[96:99], v[174:177], v[198:201], v[96:99]
	v_mfma_f32_16x16x32_bf16 v[84:87], v[166:169], v[210:213], v[84:87]
	v_mfma_f32_16x16x32_bf16 v[80:83], v[174:177], v[210:213], v[80:83]
	v_mfma_f32_16x16x32_bf16 v[68:71], v[166:169], v[218:221], v[68:71]
	v_mfma_f32_16x16x32_bf16 v[64:67], v[174:177], v[218:221], v[64:67]
	s_setprio 0
	s_barrier
	s_add_i32 s51, s51, s35
	v_lshl_add_u64 v[150:151], s[28:29], 0, v[188:189]
	s_mov_b32 m0, s51
	ds_read_b128 v[178:181], v156 offset:16384
	ds_read_b128 v[182:185], v156 offset:17408
	ds_read_b128 v[194:197], v156 offset:18432
	ds_read_b128 v[198:201], v156 offset:19456
	ds_read_b128 v[202:205], v156 offset:20480
	ds_read_b128 v[210:213], v156 offset:21504
	ds_read_b128 v[214:217], v156 offset:22528
	ds_read_b128 v[218:221], v156 offset:23552
	global_load_lds_dwordx4 v[150:151], off
	s_add_i32 m0, s51, 0x2000
	s_add_u32 s52, s28, 0x40000
	v_lshl_add_u64 v[186:187], s[28:29], 0, v[140:141]
	s_addc_u32 s53, s29, 0
	s_add_i32 s51, s54, s35
	global_load_lds_dwordx4 v[186:187], off
	v_lshl_add_u64 v[190:191], s[52:53], 0, v[188:189]
	s_mov_b32 m0, s51
	v_lshl_add_u64 v[222:223], s[30:31], 0, v[138:139]
	global_load_lds_dwordx4 v[190:191], off
	v_lshl_add_u64 v[190:191], s[52:53], 0, v[140:141]
	s_add_i32 m0, s51, 0x2000
	s_nop 0
	global_load_lds_dwordx4 v[190:191], off
	v_lshl_add_u64 v[190:191], s[30:31], 0, v[136:137]
	s_mov_b32 m0, s38
	s_nop 0
	global_load_lds_dwordx4 v[190:191], off
	s_mov_b32 m0, s39
	s_nop 0
	global_load_lds_dwordx4 v[222:223], off
	s_waitcnt vmcnt(8)
	s_waitcnt lgkmcnt(0)
	s_barrier
; #define PG8_STAGE(bufoff, gbase, voff) do { _Pragma("unroll") for (int _i = 0; _i < 2; ++_i) \
;         __builtin_amdgcn_global_load_lds((const unsigned*)((const char*)(gbase) + (voff)[_i]), (PG8_LAS unsigned*)(lds + (bufoff) + ldsw + _i * 8192), 16, 0, 0); } while (0)
; #define PG8_LDA(dst, b, h) do { _Pragma("unroll") for (int m = 0; m < 4; ++m) _Pragma("unroll") for (int k = 0; k < 2; ++k) dst[m][k] = *(const PG8_LAS bf16x8*)(lds + PG8_SA(b, h) + aoff + m * 2048 + k * 1024); } while (0)
; #define PG8_LDB(dst, b, h) do { _Pragma("unroll") for (int n = 0; n < 2; ++n) _Pragma("unroll") for (int k = 0; k < 2; ++k) dst[n][k] = *(const PG8_LAS bf16x8*)(lds + PG8_SB(b, h) + boff + n * 2048 + k * 1024); } while (0)
; #define PG8_MMA(ai, bj, At, Bt) do { __builtin_amdgcn_s_setprio(1); _Pragma("unroll") for (int m = 0; m < 4; ++m) _Pragma("unroll") for (int n = 0; n < 2; ++n) _Pragma("unroll") for (int k = 0; k < 2; ++k) \
;         acc[ai][bj][m][n] = __builtin_amdgcn_mfma_f32_16x16x32_bf16(Bt[n][k], At[m][k], acc[ai][bj][m][n], 0, 0, 0); __builtin_amdgcn_s_setprio(0); } while (0)
; #define PG8_WAIT_V(n) asm volatile("s_waitcnt vmcnt(" #n ")" ::: "memory")
; #define PG8_WAIT_L(n) asm volatile("s_waitcnt lgkmcnt(" #n ")" ::: "memory")
; #define PG8_BAR __builtin_amdgcn_s_barrier()
; #define PG8_SCHED __builtin_amdgcn_sched_barrier(0)
; template <class Epi, class Sched, bool ALIGN_EPI = false, bool SP2 = false>
; __device__ __forceinline__ void gemm_phase(PG8_LAS unsigned char* lds, const Gemm g, const Sched& S, const Epi& E) {
;     ...
;             PG8_WAIT_V(8); PG8_WAIT_L(0); PG8_BAR; PG8_MMA(1, 0, At, B0); PG8_MMA(1, 1, At, B1); PG8_BAR; PG8_SCHED;
;             PG8_LDB(B0, 1, 0); PG8_LDB(B1, 1, 1); PG8_SCHED; PG8_LDA(At, 1, 0); PG8_STAGE(PG8_SA(0, 1), a2 + hstep, voffA);
;             PG8_WAIT_V(8); PG8_WAIT_L(0); PG8_BAR; PG8_MMA(0, 0, At, B0); PG8_MMA(0, 1, At, B1); PG8_BAR; PG8_SCHED;
;             PG8_LDA(At, 1, 1); PG8_STAGE(PG8_SB(1, 0), b3, voffB); PG8_STAGE(PG8_SB(1, 1), b3 + hstep, voffB); PG8_STAGE(PG8_SA(1, 0), a3, voffA);
;             PG8_WAIT_V(8); PG8_WAIT_L(0); PG8_BAR; PG8_MMA(1, 0, At, B0); PG8_MMA(1, 1, At, B1); PG8_BAR; PG8_SCHED;
	s_setprio 1
	s_waitcnt lgkmcnt(0)
	v_mfma_f32_16x16x32_bf16 v[60:63], v[128:131], v[178:181], v[60:63]
	v_mfma_f32_16x16x32_bf16 v[56:59], v[146:149], v[178:181], v[56:59]
	v_mfma_f32_16x16x32_bf16 v[44:47], v[128:131], v[194:197], v[44:47]
	v_mfma_f32_16x16x32_bf16 v[40:43], v[146:149], v[194:197], v[40:43]
	v_mfma_f32_16x16x32_bf16 v[28:31], v[128:131], v[202:205], v[28:31]
	v_mfma_f32_16x16x32_bf16 v[24:27], v[146:149], v[202:205], v[24:27]
	v_mfma_f32_16x16x32_bf16 v[12:15], v[128:131], v[214:217], v[12:15]
	v_mfma_f32_16x16x32_bf16 v[8:11], v[146:149], v[214:217], v[8:11]
	v_mfma_f32_16x16x32_bf16 v[60:63], v[132:135], v[182:185], v[60:63]
	v_mfma_f32_16x16x32_bf16 v[56:59], v[158:161], v[182:185], v[56:59]
	v_mfma_f32_16x16x32_bf16 v[44:47], v[132:135], v[198:201], v[44:47]
	v_mfma_f32_16x16x32_bf16 v[40:43], v[158:161], v[198:201], v[40:43]
	v_mfma_f32_16x16x32_bf16 v[28:31], v[132:135], v[210:213], v[28:31]
	v_mfma_f32_16x16x32_bf16 v[24:27], v[158:161], v[210:213], v[24:27]
	v_mfma_f32_16x16x32_bf16 v[12:15], v[132:135], v[218:221], v[12:15]
	v_mfma_f32_16x16x32_bf16 v[8:11], v[158:161], v[218:221], v[8:11]
	s_setprio 0
	s_setprio 1
	v_mfma_f32_16x16x32_bf16 v[52:55], v[162:165], v[178:181], v[52:55]
	v_mfma_f32_16x16x32_bf16 v[48:51], v[170:173], v[178:181], v[48:51]
	v_mfma_f32_16x16x32_bf16 v[36:39], v[162:165], v[194:197], v[36:39]
	v_mfma_f32_16x16x32_bf16 v[32:35], v[170:173], v[194:197], v[32:35]
	v_mfma_f32_16x16x32_bf16 v[20:23], v[162:165], v[202:205], v[20:23]
	v_mfma_f32_16x16x32_bf16 v[16:19], v[170:173], v[202:205], v[16:19]
	v_mfma_f32_16x16x32_bf16 v[4:7], v[162:165], v[214:217], v[4:7]
	v_mfma_f32_16x16x32_bf16 v[0:3], v[170:173], v[214:217], v[0:3]
	v_mfma_f32_16x16x32_bf16 v[52:55], v[166:169], v[182:185], v[52:55]
	v_mfma_f32_16x16x32_bf16 v[48:51], v[174:177], v[182:185], v[48:51]
	v_mfma_f32_16x16x32_bf16 v[36:39], v[166:169], v[198:201], v[36:39]
	v_mfma_f32_16x16x32_bf16 v[32:35], v[174:177], v[198:201], v[32:35]
	v_mfma_f32_16x16x32_bf16 v[20:23], v[166:169], v[210:213], v[20:23]
	v_mfma_f32_16x16x32_bf16 v[16:19], v[174:177], v[210:213], v[16:19]
	v_mfma_f32_16x16x32_bf16 v[4:7], v[166:169], v[218:221], v[4:7]
	v_mfma_f32_16x16x32_bf16 v[0:3], v[174:177], v[218:221], v[0:3]
	s_setprio 0
	s_barrier
	s_add_i32 s51, 0, 0x18000
	v_add_u32_e32 v157, s51, v154
	s_add_i32 s52, 0, 0x1c000
	ds_read_b128 v[128:131], v157
	ds_read_b128 v[132:135], v157 offset:1024
	ds_read_b128 v[146:149], v157 offset:2048
	ds_read_b128 v[158:161], v157 offset:3072
	v_add_u32_e32 v157, s52, v154
	ds_read_b128 v[162:165], v157
	ds_read_b128 v[166:169], v157 offset:1024
	ds_read_b128 v[170:173], v157 offset:2048
	ds_read_b128 v[174:177], v157 offset:3072
	s_add_u32 s30, s30, 0x40000
	s_addc_u32 s31, s31, 0
	s_mov_b32 m0, s40
	v_lshl_add_u64 v[224:225], s[30:31], 0, v[136:137]
	ds_read_b128 v[178:181], v156 offset:32768
	ds_read_b128 v[182:185], v156 offset:33792
	ds_read_b128 v[194:197], v156 offset:34816
	ds_read_b128 v[198:201], v156 offset:35840
	ds_read_b128 v[202:205], v156 offset:36864
	ds_read_b128 v[210:213], v156 offset:37888
	ds_read_b128 v[214:217], v156 offset:38912
	ds_read_b128 v[218:221], v156 offset:39936
	global_load_lds_dwordx4 v[224:225], off
	v_lshl_add_u64 v[224:225], s[30:31], 0, v[138:139]
	s_mov_b32 m0, s41
	s_nop 0
	global_load_lds_dwordx4 v[224:225], off
	s_waitcnt vmcnt(8)
	s_waitcnt lgkmcnt(0)
	s_barrier
	s_setprio 1
	s_waitcnt lgkmcnt(0)
	v_mfma_f32_16x16x32_bf16 v[124:127], v[128:131], v[178:181], v[124:127]
	v_mfma_f32_16x16x32_bf16 v[120:123], v[146:149], v[178:181], v[120:123]
	v_mfma_f32_16x16x32_bf16 v[108:111], v[128:131], v[194:197], v[108:111]
	v_mfma_f32_16x16x32_bf16 v[104:107], v[146:149], v[194:197], v[104:107]
	v_mfma_f32_16x16x32_bf16 v[92:95], v[128:131], v[202:205], v[92:95]
	v_mfma_f32_16x16x32_bf16 v[88:91], v[146:149], v[202:205], v[88:91]
	v_mfma_f32_16x16x32_bf16 v[76:79], v[128:131], v[214:217], v[76:79]
	v_mfma_f32_16x16x32_bf16 v[72:75], v[146:149], v[214:217], v[72:75]
	v_mfma_f32_16x16x32_bf16 v[124:127], v[132:135], v[182:185], v[124:127]
	v_mfma_f32_16x16x32_bf16 v[120:123], v[158:161], v[182:185], v[120:123]
	v_mfma_f32_16x16x32_bf16 v[108:111], v[132:135], v[198:201], v[108:111]
	v_mfma_f32_16x16x32_bf16 v[104:107], v[158:161], v[198:201], v[104:107]
	v_mfma_f32_16x16x32_bf16 v[92:95], v[132:135], v[210:213], v[92:95]
	v_mfma_f32_16x16x32_bf16 v[88:91], v[158:161], v[210:213], v[88:91]
	v_mfma_f32_16x16x32_bf16 v[76:79], v[132:135], v[218:221], v[76:79]
	v_mfma_f32_16x16x32_bf16 v[72:75], v[158:161], v[218:221], v[72:75]
	s_setprio 0
	s_setprio 1
	v_mfma_f32_16x16x32_bf16 v[116:119], v[162:165], v[178:181], v[116:119]
	v_mfma_f32_16x16x32_bf16 v[112:115], v[170:173], v[178:181], v[112:115]
	v_mfma_f32_16x16x32_bf16 v[100:103], v[162:165], v[194:197], v[100:103]
	v_mfma_f32_16x16x32_bf16 v[96:99], v[170:173], v[194:197], v[96:99]
	v_mfma_f32_16x16x32_bf16 v[84:87], v[162:165], v[202:205], v[84:87]
	v_mfma_f32_16x16x32_bf16 v[80:83], v[170:173], v[202:205], v[80:83]
	v_mfma_f32_16x16x32_bf16 v[68:71], v[162:165], v[214:217], v[68:71]
	v_mfma_f32_16x16x32_bf16 v[64:67], v[170:173], v[214:217], v[64:67]
	v_mfma_f32_16x16x32_bf16 v[116:119], v[166:169], v[182:185], v[116:119]
	v_mfma_f32_16x16x32_bf16 v[112:115], v[174:177], v[182:185], v[112:115]
	v_mfma_f32_16x16x32_bf16 v[100:103], v[166:169], v[198:201], v[100:103]
	v_mfma_f32_16x16x32_bf16 v[96:99], v[174:177], v[198:201], v[96:99]
	v_mfma_f32_16x16x32_bf16 v[84:87], v[166:169], v[210:213], v[84:87]
	v_mfma_f32_16x16x32_bf16 v[80:83], v[174:177], v[210:213], v[80:83]
	v_mfma_f32_16x16x32_bf16 v[68:71], v[166:169], v[218:221], v[68:71]
	v_mfma_f32_16x16x32_bf16 v[64:67], v[174:177], v[218:221], v[64:67]
	s_setprio 0
	s_barrier
; __device__ __forceinline__ u32x4 pack8(const f32x4 a, const f32x4 b) { u32x4 w; w.x = cvt_pk_bf16(a[0], a[1]); w.y = cvt_pk_bf16(a[2], a[3]); w.z = cvt_pk_bf16(b[0], b[1]); w.w = cvt_pk_bf16(b[2], b[3]); return w; }
; #define PG8_STAGE(bufoff, gbase, voff) do { _Pragma("unroll") for (int _i = 0; _i < 2; ++_i) \
;         __builtin_amdgcn_global_load_lds((const unsigned*)((const char*)(gbase) + (voff)[_i]), (PG8_LAS unsigned*)(lds + (bufoff) + ldsw + _i * 8192), 16, 0, 0); } while (0)
; #define PG8_LDA(dst, b, h) do { _Pragma("unroll") for (int m = 0; m < 4; ++m) _Pragma("unroll") for (int k = 0; k < 2; ++k) dst[m][k] = *(const PG8_LAS bf16x8*)(lds + PG8_SA(b, h) + aoff + m * 2048 + k * 1024); } while (0)
; #define PG8_WAIT_V(n) asm volatile("s_waitcnt vmcnt(" #n ")" ::: "memory")
;     __device__ __forceinline__ void operator()(const f32x4 (&acc)[2][2][4][2], const Unit& u, int wr, int wc, int fr, int fq) const {
;         const int row0 = u.pm * BM + wr * 64 + fr; const int col0 = u.pn * BM + wc * 32 + 8 * fq;
;         const bool part = u.nkt != nkt_full;
;         bf16_t* pbase = PART + ((long)(u.kt0 / u.nkt) * prows - row0p) * 1024;
; #pragma unroll
;         for (int ai = 0; ai < 2; ++ai)
; #pragma unroll
;             for (int m = 0; m < 4; ++m) { const size_t ro = (size_t)(row0 + ai * HALF + m * 16) * 1024 + col0;
; #pragma unroll
;                 for (int bj = 0; bj < 2; ++bj) { const size_t o = ro + bj * HALF;
;                     if (part) *(u32x4*)(pbase + o) = pack8(acc[ai][bj][m][0], acc[ai][bj][m][1]);
;                     else { f32x4 r0, r1;
;                         if (X32) { r0 = *(const f32x4*)(X32 + o); r1 = *(const f32x4*)(X32 + o + 4); }
;                         else { const u32x4 hw = *(const u32x4*)(H + o); r0 = (f32x4){bflo(hw.x), bfhi(hw.x), bflo(hw.y), bfhi(hw.y)}; r1 = (f32x4){bflo(hw.z), bfhi(hw.z), bflo(hw.w), bfhi(hw.w)}; }
; template <class Epi, class Sched, bool ALIGN_EPI = false, bool SP2 = false>
; __device__ __forceinline__ void gemm_phase(PG8_LAS unsigned char* lds, const Gemm g, const Sched& S, const Epi& E) {
;     ...
;             PG8_LDA(At, 1, 1); PG8_STAGE(PG8_SB(1, 0), b3, voffB); PG8_STAGE(PG8_SB(1, 1), b3 + hstep, voffB); PG8_STAGE(PG8_SA(1, 0), a3, voffA);
;             PG8_WAIT_V(8); PG8_WAIT_L(0); PG8_BAR; PG8_MMA(1, 0, At, B0); PG8_MMA(1, 1, At, B1); PG8_BAR; PG8_SCHED;
	s_add_i32 s30, s51, s35
	v_lshl_add_u64 v[150:151], v[150:151], 0, s[56:57]
	s_mov_b32 m0, s30
	ds_read_b128 v[178:181], v156 offset:49152
	ds_read_b128 v[182:185], v156 offset:50176
	ds_read_b128 v[194:197], v156 offset:51200
	ds_read_b128 v[198:201], v156 offset:52224
	ds_read_b128 v[202:205], v156 offset:53248
	ds_read_b128 v[210:213], v156 offset:54272
	ds_read_b128 v[214:217], v156 offset:55296
	ds_read_b128 v[218:221], v156 offset:56320
	global_load_lds_dwordx4 v[150:151], off
	s_add_i32 m0, s30, 0x2000
	s_add_u32 s28, s28, 0x40080
	v_lshl_add_u64 v[150:151], v[186:187], 0, s[56:57]
	s_addc_u32 s29, s29, 0
	s_add_i32 s30, s52, s35
	global_load_lds_dwordx4 v[150:151], off
	v_lshl_add_u64 v[150:151], s[28:29], 0, v[188:189]
	s_mov_b32 m0, s30
	s_nop 0
	global_load_lds_dwordx4 v[150:151], off
	v_lshl_add_u64 v[150:151], s[28:29], 0, v[140:141]
	s_add_i32 m0, s30, 0x2000
	s_nop 0
	global_load_lds_dwordx4 v[150:151], off
	v_lshl_add_u64 v[150:151], v[190:191], 0, s[56:57]
	s_mov_b32 m0, s42
	s_nop 0
	global_load_lds_dwordx4 v[150:151], off
	v_lshl_add_u64 v[150:151], v[222:223], 0, s[56:57]
	s_mov_b32 m0, s43
	s_nop 0
	global_load_lds_dwordx4 v[150:151], off
	s_waitcnt vmcnt(8)
	s_waitcnt lgkmcnt(0)
	s_barrier
	s_setprio 1
	s_waitcnt lgkmcnt(0)
	v_mfma_f32_16x16x32_bf16 v[60:63], v[128:131], v[178:181], v[60:63]
	v_mfma_f32_16x16x32_bf16 v[56:59], v[146:149], v[178:181], v[56:59]
	v_mfma_f32_16x16x32_bf16 v[44:47], v[128:131], v[194:197], v[44:47]
	v_mfma_f32_16x16x32_bf16 v[40:43], v[146:149], v[194:197], v[40:43]
	v_mfma_f32_16x16x32_bf16 v[28:31], v[128:131], v[202:205], v[28:31]
	v_mfma_f32_16x16x32_bf16 v[24:27], v[146:149], v[202:205], v[24:27]
	v_mfma_f32_16x16x32_bf16 v[12:15], v[128:131], v[214:217], v[12:15]
	v_mfma_f32_16x16x32_bf16 v[8:11], v[146:149], v[214:217], v[8:11]
	v_mfma_f32_16x16x32_bf16 v[60:63], v[132:135], v[182:185], v[60:63]
	v_mfma_f32_16x16x32_bf16 v[56:59], v[158:161], v[182:185], v[56:59]
	v_mfma_f32_16x16x32_bf16 v[44:47], v[132:135], v[198:201], v[44:47]
	v_mfma_f32_16x16x32_bf16 v[40:43], v[158:161], v[198:201], v[40:43]
	v_mfma_f32_16x16x32_bf16 v[28:31], v[132:135], v[210:213], v[28:31]
	v_mfma_f32_16x16x32_bf16 v[24:27], v[158:161], v[210:213], v[24:27]
	v_mfma_f32_16x16x32_bf16 v[12:15], v[132:135], v[218:221], v[12:15]
	v_mfma_f32_16x16x32_bf16 v[8:11], v[158:161], v[218:221], v[8:11]
	s_setprio 0
	s_setprio 1
	v_mfma_f32_16x16x32_bf16 v[52:55], v[162:165], v[178:181], v[52:55]
	v_mfma_f32_16x16x32_bf16 v[48:51], v[170:173], v[178:181], v[48:51]
	v_mfma_f32_16x16x32_bf16 v[36:39], v[162:165], v[194:197], v[36:39]
	v_mfma_f32_16x16x32_bf16 v[32:35], v[170:173], v[194:197], v[32:35]
	v_mfma_f32_16x16x32_bf16 v[20:23], v[162:165], v[202:205], v[20:23]
	v_mfma_f32_16x16x32_bf16 v[16:19], v[170:173], v[202:205], v[16:19]
	v_mfma_f32_16x16x32_bf16 v[4:7], v[162:165], v[214:217], v[4:7]
	v_mfma_f32_16x16x32_bf16 v[0:3], v[170:173], v[214:217], v[0:3]
	v_mfma_f32_16x16x32_bf16 v[52:55], v[166:169], v[182:185], v[52:55]
	v_mfma_f32_16x16x32_bf16 v[48:51], v[174:177], v[182:185], v[48:51]
	v_mfma_f32_16x16x32_bf16 v[36:39], v[166:169], v[198:201], v[36:39]
	v_mfma_f32_16x16x32_bf16 v[32:35], v[174:177], v[198:201], v[32:35]
	v_mfma_f32_16x16x32_bf16 v[20:23], v[166:169], v[210:213], v[20:23]
	v_mfma_f32_16x16x32_bf16 v[16:19], v[174:177], v[210:213], v[16:19]
	v_mfma_f32_16x16x32_bf16 v[4:7], v[166:169], v[218:221], v[4:7]
	v_mfma_f32_16x16x32_bf16 v[0:3], v[174:177], v[218:221], v[0:3]
	s_setprio 0
	s_barrier
	s_add_i32 s28, s1, 2
	s_add_u32 s26, s26, 0x100
	s_addc_u32 s27, s27, 0
	s_add_u32 s49, s49, 0x100
	s_addc_u32 s50, s50, 0
	s_cmp_ge_u32 s1, s9
	s_mov_b32 s1, s28
	s_cbranch_scc0 .LBB0_874
	s_cmp_lg_u32 s9, 16
	s_cbranch_scc1 .Lp4_nopre
	v_lshl_add_u32 v150, s0, 8, v153
	v_lshl_or_b32 v151, s8, 8, v155
	v_lshlrev_b32_e32 v150, 11, v150
	v_lshl_add_u32 v150, v151, 1, v150
	v_readlane_b32 s0, v254, 17
	v_readlane_b32 s1, v254, 18
	s_and_b64 vcc, exec, s[14:15]
	s_cbranch_vccz .Lp4_pre_h
	v_lshlrev_b32_e32 v151, 1, v150
	s_add_u32 s26, s2, 0x0
	s_addc_u32 s27, s3, 0
	global_load_dwordx4 v[128:131], v151, s[26:27]
	global_load_dwordx4 v[132:135], v151, s[26:27] offset:16
	global_load_dwordx4 v[146:149], v151, s[26:27] offset:512
	global_load_dwordx4 v[158:161], v151, s[26:27] offset:528
	s_add_u32 s26, s2, 0x10000
	s_addc_u32 s27, s3, 0
	global_load_dwordx4 v[162:165], v151, s[26:27]
	global_load_dwordx4 v[166:169], v151, s[26:27] offset:16
	global_load_dwordx4 v[170:173], v151, s[26:27] offset:512
	global_load_dwordx4 v[174:177], v151, s[26:27] offset:528
	s_add_u32 s26, s2, 0x20000
	s_addc_u32 s27, s3, 0
	global_load_dwordx4 v[178:181], v151, s[26:27]
	global_load_dwordx4 v[182:185], v151, s[26:27] offset:16
	global_load_dwordx4 v[194:197], v151, s[26:27] offset:512
	global_load_dwordx4 v[198:201], v151, s[26:27] offset:528
	s_add_u32 s26, s2, 0x30000
	s_addc_u32 s27, s3, 0
	global_load_dwordx4 v[202:205], v151, s[26:27]
	global_load_dwordx4 v[210:213], v151, s[26:27] offset:16
	global_load_dwordx4 v[214:217], v151, s[26:27] offset:512
	global_load_dwordx4 v[218:221], v151, s[26:27] offset:528
	s_branch .Lp4_nopre
; __device__ __forceinline__ u32x4 pack8(const f32x4 a, const f32x4 b) { u32x4 w; w.x = cvt_pk_bf16(a[0], a[1]); w.y = cvt_pk_bf16(a[2], a[3]); w.z = cvt_pk_bf16(b[0], b[1]); w.w = cvt_pk_bf16(b[2], b[3]); return w; }
;     __device__ __forceinline__ void operator()(const f32x4 (&acc)[2][2][4][2], const Unit& u, int wr, int wc, int fr, int fq) const {
;     ...
;             for (int m = 0; m < 4; ++m) { const size_t ro = (size_t)(row0 + ai * HALF + m * 16) * 1024 + col0;
; #pragma unroll
;                 for (int bj = 0; bj < 2; ++bj) { const size_t o = ro + bj * HALF;
;                     if (part) *(u32x4*)(pbase + o) = pack8(acc[ai][bj][m][0], acc[ai][bj][m][1]);
;                     else { f32x4 r0, r1;
;                         if (X32) { r0 = *(const f32x4*)(X32 + o); r1 = *(const f32x4*)(X32 + o + 4); }
;                         else { const u32x4 hw = *(const u32x4*)(H + o); r0 = (f32x4){bflo(hw.x), bfhi(hw.x), bflo(hw.y), bfhi(hw.y)}; r1 = (f32x4){bflo(hw.z), bfhi(hw.z), bflo(hw.w), bfhi(hw.w)}; }
;                         *(u32x4*)(H + o) = pack8(r0 + acc[ai][bj][m][0], r1 + acc[ai][bj][m][1]); } }
.Lp4_pre_h:
	s_add_u32 s8, s0, 0x0
	s_addc_u32 s9, s1, 0
	global_load_dwordx4 v[128:131], v150, s[8:9]
	global_load_dwordx4 v[132:135], v150, s[8:9] offset:256
	s_add_u32 s8, s0, 0x8000
	s_addc_u32 s9, s1, 0
	global_load_dwordx4 v[146:149], v150, s[8:9]
	global_load_dwordx4 v[158:161], v150, s[8:9] offset:256
	s_add_u32 s8, s0, 0x10000
	s_addc_u32 s9, s1, 0
	global_load_dwordx4 v[162:165], v150, s[8:9]
	global_load_dwordx4 v[166:169], v150, s[8:9] offset:256
	s_add_u32 s8, s0, 0x18000
	s_addc_u32 s9, s1, 0
	global_load_dwordx4 v[170:173], v150, s[8:9]
	global_load_dwordx4 v[174:177], v150, s[8:9] offset:256
	s_add_u32 s8, s0, 0x40000
	s_addc_u32 s9, s1, 0
	global_load_dwordx4 v[178:181], v150, s[8:9]
	global_load_dwordx4 v[182:185], v150, s[8:9] offset:256
	s_add_u32 s8, s0, 0x48000
	s_addc_u32 s9, s1, 0
	global_load_dwordx4 v[194:197], v150, s[8:9]
	global_load_dwordx4 v[198:201], v150, s[8:9] offset:256
	s_add_u32 s8, s0, 0x50000
	s_addc_u32 s9, s1, 0
	global_load_dwordx4 v[202:205], v150, s[8:9]
	global_load_dwordx4 v[210:213], v150, s[8:9] offset:256
	s_add_u32 s8, s0, 0x58000
	s_addc_u32 s9, s1, 0
	global_load_dwordx4 v[214:217], v150, s[8:9]
	global_load_dwordx4 v[218:221], v150, s[8:9] offset:256
	s_mov_b32 s9, 16
.Lp4_nopre:
	s_and_b64 vcc, exec, s[12:13]
	s_cbranch_vccz .LBB0_877
	s_barrier
.LBB0_877:
	s_cmp_lg_u32 s9, 16
	s_cbranch_scc1 .Lp4_slow
	s_and_b64 vcc, exec, s[14:15]
	s_cbranch_vccz .Lp4_proc_h
	s_add_u32 s8, s0, 0x0
	s_addc_u32 s9, s1, 0
	s_add_u32 s28, s2, 0x80000
	s_addc_u32 s29, s3, 0
	s_waitcnt vmcnt(14)
	v_add_f32_e32 v124, v124, v128
	v_add_f32_e32 v125, v125, v129
	v_add_f32_e32 v126, v126, v130
	v_add_f32_e32 v127, v127, v131
	v_add_f32_e32 v120, v120, v132
	v_add_f32_e32 v121, v121, v133
	v_add_f32_e32 v122, v122, v134
	v_add_f32_e32 v123, v123, v135
	v_cvt_pk_bf16_f32 v128, v124, v125
	v_cvt_pk_bf16_f32 v129, v126, v127
	v_cvt_pk_bf16_f32 v130, v120, v121
	v_cvt_pk_bf16_f32 v131, v122, v123
	global_store_dwordx4 v150, v[128:131], s[8:9]
	global_load_dwordx4 v[132:135], v151, s[28:29] offset:16
	global_load_dwordx4 v[128:131], v151, s[28:29]
	s_waitcnt vmcnt(15)
	v_add_f32_e32 v116, v116, v146
	v_add_f32_e32 v117, v117, v147
	v_add_f32_e32 v118, v118, v148
	v_add_f32_e32 v119, v119, v149
	v_add_f32_e32 v112, v112, v158
	v_add_f32_e32 v113, v113, v159
	v_add_f32_e32 v114, v114, v160
	v_add_f32_e32 v115, v115, v161
	v_cvt_pk_bf16_f32 v146, v116, v117
	v_cvt_pk_bf16_f32 v147, v118, v119
	v_cvt_pk_bf16_f32 v148, v112, v113
	v_cvt_pk_bf16_f32 v149, v114, v115
	global_store_dwordx4 v150, v[146:149], s[8:9] offset:256
	global_load_dwordx4 v[158:161], v151, s[28:29] offset:528
	global_load_dwordx4 v[146:149], v151, s[28:29] offset:512
	s_add_u32 s8, s0, 0x8000
	s_addc_u32 s9, s1, 0
	s_add_u32 s28, s2, 0x90000
	s_addc_u32 s29, s3, 0
	s_waitcnt vmcnt(16)
	v_add_f32_e32 v108, v108, v162
	v_add_f32_e32 v109, v109, v163
	v_add_f32_e32 v110, v110, v164
	v_add_f32_e32 v111, v111, v165
	v_add_f32_e32 v104, v104, v166
	v_add_f32_e32 v105, v105, v167
	v_add_f32_e32 v106, v106, v168
	v_add_f32_e32 v107, v107, v169
	v_cvt_pk_bf16_f32 v162, v108, v109
	v_cvt_pk_bf16_f32 v163, v110, v111
	v_cvt_pk_bf16_f32 v164, v104, v105
	v_cvt_pk_bf16_f32 v165, v106, v107
	global_store_dwordx4 v150, v[162:165], s[8:9]
	global_load_dwordx4 v[166:169], v151, s[28:29] offset:16
	global_load_dwordx4 v[162:165], v151, s[28:29]
	s_waitcnt vmcnt(17)
	v_add_f32_e32 v100, v100, v170
	v_add_f32_e32 v101, v101, v171
	v_add_f32_e32 v102, v102, v172
	v_add_f32_e32 v103, v103, v173
	v_add_f32_e32 v96, v96, v174
	v_add_f32_e32 v97, v97, v175
	v_add_f32_e32 v98, v98, v176
	v_add_f32_e32 v99, v99, v177
	v_cvt_pk_bf16_f32 v170, v100, v101
	v_cvt_pk_bf16_f32 v171, v102, v103
	v_cvt_pk_bf16_f32 v172, v96, v97
	v_cvt_pk_bf16_f32 v173, v98, v99
	global_store_dwordx4 v150, v[170:173], s[8:9] offset:256
	global_load_dwordx4 v[174:177], v151, s[28:29] offset:528
	global_load_dwordx4 v[170:173], v151, s[28:29] offset:512
	s_add_u32 s8, s0, 0x10000
	s_addc_u32 s9, s1, 0
	s_add_u32 s28, s2, 0xa0000
	s_addc_u32 s29, s3, 0
	s_waitcnt vmcnt(18)
	v_add_f32_e32 v92, v92, v178
	v_add_f32_e32 v93, v93, v179
	v_add_f32_e32 v94, v94, v180
	v_add_f32_e32 v95, v95, v181
	v_add_f32_e32 v88, v88, v182
	v_add_f32_e32 v89, v89, v183
	v_add_f32_e32 v90, v90, v184
	v_add_f32_e32 v91, v91, v185
	v_cvt_pk_bf16_f32 v178, v92, v93
	v_cvt_pk_bf16_f32 v179, v94, v95
	v_cvt_pk_bf16_f32 v180, v88, v89
	v_cvt_pk_bf16_f32 v181, v90, v91
	global_store_dwordx4 v150, v[178:181], s[8:9]
	global_load_dwordx4 v[182:185], v151, s[28:29] offset:16
	global_load_dwordx4 v[178:181], v151, s[28:29]
	s_waitcnt vmcnt(19)
	v_add_f32_e32 v84, v84, v194
	v_add_f32_e32 v85, v85, v195
	v_add_f32_e32 v86, v86, v196
	v_add_f32_e32 v87, v87, v197
	v_add_f32_e32 v80, v80, v198
	v_add_f32_e32 v81, v81, v199
	v_add_f32_e32 v82, v82, v200
	v_add_f32_e32 v83, v83, v201
	v_cvt_pk_bf16_f32 v194, v84, v85
	v_cvt_pk_bf16_f32 v195, v86, v87
	v_cvt_pk_bf16_f32 v196, v80, v81
	v_cvt_pk_bf16_f32 v197, v82, v83
	global_store_dwordx4 v150, v[194:197], s[8:9] offset:256
	global_load_dwordx4 v[198:201], v151, s[28:29] offset:528
	global_load_dwordx4 v[194:197], v151, s[28:29] offset:512
	s_add_u32 s8, s0, 0x18000
	s_addc_u32 s9, s1, 0
	s_add_u32 s28, s2, 0xb0000
	s_addc_u32 s29, s3, 0
	s_waitcnt vmcnt(20)
	v_add_f32_e32 v76, v76, v202
	v_add_f32_e32 v77, v77, v203
	v_add_f32_e32 v78, v78, v204
	v_add_f32_e32 v79, v79, v205
	v_add_f32_e32 v72, v72, v210
	v_add_f32_e32 v73, v73, v211
	v_add_f32_e32 v74, v74, v212
	v_add_f32_e32 v75, v75, v213
	v_cvt_pk_bf16_f32 v202, v76, v77
	v_cvt_pk_bf16_f32 v203, v78, v79
	v_cvt_pk_bf16_f32 v204, v72, v73
	v_cvt_pk_bf16_f32 v205, v74, v75
	global_store_dwordx4 v150, v[202:205], s[8:9]
	global_load_dwordx4 v[210:213], v151, s[28:29] offset:16
	global_load_dwordx4 v[202:205], v151, s[28:29]
	s_waitcnt vmcnt(21)
; __device__ __forceinline__ u32x4 pack8(const f32x4 a, const f32x4 b) { u32x4 w; w.x = cvt_pk_bf16(a[0], a[1]); w.y = cvt_pk_bf16(a[2], a[3]); w.z = cvt_pk_bf16(b[0], b[1]); w.w = cvt_pk_bf16(b[2], b[3]); return w; }
;     __device__ __forceinline__ void operator()(const f32x4 (&acc)[2][2][4][2], const Unit& u, int wr, int wc, int fr, int fq) const {
;     ...
;             for (int m = 0; m < 4; ++m) { const size_t ro = (size_t)(row0 + ai * HALF + m * 16) * 1024 + col0;
; #pragma unroll
;                 for (int bj = 0; bj < 2; ++bj) { const size_t o = ro + bj * HALF;
;                     if (part) *(u32x4*)(pbase + o) = pack8(acc[ai][bj][m][0], acc[ai][bj][m][1]);
;                     else { f32x4 r0, r1;
;                         if (X32) { r0 = *(const f32x4*)(X32 + o); r1 = *(const f32x4*)(X32 + o + 4); }
;                         else { const u32x4 hw = *(const u32x4*)(H + o); r0 = (f32x4){bflo(hw.x), bfhi(hw.x), bflo(hw.y), bfhi(hw.y)}; r1 = (f32x4){bflo(hw.z), bfhi(hw.z), bflo(hw.w), bfhi(hw.w)}; }
;                         *(u32x4*)(H + o) = pack8(r0 + acc[ai][bj][m][0], r1 + acc[ai][bj][m][1]); } }
;                 asm volatile("" ::: "memory"); }
	v_add_f32_e32 v68, v68, v214
	v_add_f32_e32 v69, v69, v215
	v_add_f32_e32 v70, v70, v216
	v_add_f32_e32 v71, v71, v217
	v_add_f32_e32 v64, v64, v218
	v_add_f32_e32 v65, v65, v219
	v_add_f32_e32 v66, v66, v220
	v_add_f32_e32 v67, v67, v221
	v_cvt_pk_bf16_f32 v214, v68, v69
	v_cvt_pk_bf16_f32 v215, v70, v71
	v_cvt_pk_bf16_f32 v216, v64, v65
	v_cvt_pk_bf16_f32 v217, v66, v67
	global_store_dwordx4 v150, v[214:217], s[8:9] offset:256
	global_load_dwordx4 v[218:221], v151, s[28:29] offset:528
	global_load_dwordx4 v[214:217], v151, s[28:29] offset:512
	s_add_u32 s8, s0, 0x40000
	s_addc_u32 s9, s1, 0
	s_waitcnt vmcnt(21)
	v_add_f32_e32 v60, v60, v128
	v_add_f32_e32 v61, v61, v129
	v_add_f32_e32 v62, v62, v130
	v_add_f32_e32 v63, v63, v131
	v_add_f32_e32 v56, v56, v132
	v_add_f32_e32 v57, v57, v133
	v_add_f32_e32 v58, v58, v134
	v_add_f32_e32 v59, v59, v135
	v_cvt_pk_bf16_f32 v128, v60, v61
	v_cvt_pk_bf16_f32 v129, v62, v63
	v_cvt_pk_bf16_f32 v130, v56, v57
	v_cvt_pk_bf16_f32 v131, v58, v59
	global_store_dwordx4 v150, v[128:131], s[8:9]
	s_waitcnt vmcnt(19)
	v_add_f32_e32 v52, v52, v146
	v_add_f32_e32 v53, v53, v147
	v_add_f32_e32 v54, v54, v148
	v_add_f32_e32 v55, v55, v149
	v_add_f32_e32 v48, v48, v158
	v_add_f32_e32 v49, v49, v159
	v_add_f32_e32 v50, v50, v160
	v_add_f32_e32 v51, v51, v161
	v_cvt_pk_bf16_f32 v146, v52, v53
	v_cvt_pk_bf16_f32 v147, v54, v55
	v_cvt_pk_bf16_f32 v148, v48, v49
	v_cvt_pk_bf16_f32 v149, v50, v51
	global_store_dwordx4 v150, v[146:149], s[8:9] offset:256
	s_add_u32 s8, s0, 0x48000
	s_addc_u32 s9, s1, 0
	s_waitcnt vmcnt(17)
	v_add_f32_e32 v44, v44, v162
	v_add_f32_e32 v45, v45, v163
	v_add_f32_e32 v46, v46, v164
	v_add_f32_e32 v47, v47, v165
	v_add_f32_e32 v40, v40, v166
	v_add_f32_e32 v41, v41, v167
	v_add_f32_e32 v42, v42, v168
	v_add_f32_e32 v43, v43, v169
	v_cvt_pk_bf16_f32 v162, v44, v45
	v_cvt_pk_bf16_f32 v163, v46, v47
	v_cvt_pk_bf16_f32 v164, v40, v41
	v_cvt_pk_bf16_f32 v165, v42, v43
	global_store_dwordx4 v150, v[162:165], s[8:9]
	s_waitcnt vmcnt(15)
	v_add_f32_e32 v36, v36, v170
	v_add_f32_e32 v37, v37, v171
	v_add_f32_e32 v38, v38, v172
	v_add_f32_e32 v39, v39, v173
	v_add_f32_e32 v32, v32, v174
	v_add_f32_e32 v33, v33, v175
	v_add_f32_e32 v34, v34, v176
	v_add_f32_e32 v35, v35, v177
	v_cvt_pk_bf16_f32 v170, v36, v37
	v_cvt_pk_bf16_f32 v171, v38, v39
	v_cvt_pk_bf16_f32 v172, v32, v33
	v_cvt_pk_bf16_f32 v173, v34, v35
	global_store_dwordx4 v150, v[170:173], s[8:9] offset:256
	s_add_u32 s8, s0, 0x50000
	s_addc_u32 s9, s1, 0
	s_waitcnt vmcnt(13)
	v_add_f32_e32 v28, v28, v178
	v_add_f32_e32 v29, v29, v179
	v_add_f32_e32 v30, v30, v180
	v_add_f32_e32 v31, v31, v181
	v_add_f32_e32 v24, v24, v182
	v_add_f32_e32 v25, v25, v183
	v_add_f32_e32 v26, v26, v184
	v_add_f32_e32 v27, v27, v185
	v_cvt_pk_bf16_f32 v178, v28, v29
	v_cvt_pk_bf16_f32 v179, v30, v31
	v_cvt_pk_bf16_f32 v180, v24, v25
	v_cvt_pk_bf16_f32 v181, v26, v27
	global_store_dwordx4 v150, v[178:181], s[8:9]
	s_waitcnt vmcnt(11)
	v_add_f32_e32 v20, v20, v194
	v_add_f32_e32 v21, v21, v195
	v_add_f32_e32 v22, v22, v196
	v_add_f32_e32 v23, v23, v197
	v_add_f32_e32 v16, v16, v198
	v_add_f32_e32 v17, v17, v199
	v_add_f32_e32 v18, v18, v200
	v_add_f32_e32 v19, v19, v201
	v_cvt_pk_bf16_f32 v194, v20, v21
	v_cvt_pk_bf16_f32 v195, v22, v23
	v_cvt_pk_bf16_f32 v196, v16, v17
	v_cvt_pk_bf16_f32 v197, v18, v19
	global_store_dwordx4 v150, v[194:197], s[8:9] offset:256
	s_add_u32 s8, s0, 0x58000
	s_addc_u32 s9, s1, 0
	s_waitcnt vmcnt(9)
	v_add_f32_e32 v12, v12, v202
	v_add_f32_e32 v13, v13, v203
	v_add_f32_e32 v14, v14, v204
	v_add_f32_e32 v15, v15, v205
	v_add_f32_e32 v8, v8, v210
	v_add_f32_e32 v9, v9, v211
	v_add_f32_e32 v10, v10, v212
	v_add_f32_e32 v11, v11, v213
	v_cvt_pk_bf16_f32 v202, v12, v13
	v_cvt_pk_bf16_f32 v203, v14, v15
	v_cvt_pk_bf16_f32 v204, v8, v9
	v_cvt_pk_bf16_f32 v205, v10, v11
	global_store_dwordx4 v150, v[202:205], s[8:9]
	s_waitcnt vmcnt(7)
	v_add_f32_e32 v4, v4, v214
	v_add_f32_e32 v5, v5, v215
	v_add_f32_e32 v6, v6, v216
	v_add_f32_e32 v7, v7, v217
	v_add_f32_e32 v0, v0, v218
	v_add_f32_e32 v1, v1, v219
	v_add_f32_e32 v2, v2, v220
	v_add_f32_e32 v3, v3, v221
	v_cvt_pk_bf16_f32 v214, v4, v5
	v_cvt_pk_bf16_f32 v215, v6, v7
	v_cvt_pk_bf16_f32 v216, v0, v1
	v_cvt_pk_bf16_f32 v217, v2, v3
	global_store_dwordx4 v150, v[214:217], s[8:9] offset:256
	s_branch .Lp4_done
; __device__ __forceinline__ u32x4 pack8(const f32x4 a, const f32x4 b) { u32x4 w; w.x = cvt_pk_bf16(a[0], a[1]); w.y = cvt_pk_bf16(a[2], a[3]); w.z = cvt_pk_bf16(b[0], b[1]); w.w = cvt_pk_bf16(b[2], b[3]); return w; }
;     __device__ __forceinline__ void operator()(const f32x4 (&acc)[2][2][4][2], const Unit& u, int wr, int wc, int fr, int fq) const {
;     ...
;             for (int m = 0; m < 4; ++m) { const size_t ro = (size_t)(row0 + ai * HALF + m * 16) * 1024 + col0;
; #pragma unroll
;                 for (int bj = 0; bj < 2; ++bj) { const size_t o = ro + bj * HALF;
;                     if (part) *(u32x4*)(pbase + o) = pack8(acc[ai][bj][m][0], acc[ai][bj][m][1]);
;                     else { f32x4 r0, r1;
;                         if (X32) { r0 = *(const f32x4*)(X32 + o); r1 = *(const f32x4*)(X32 + o + 4); }
;                         else { const u32x4 hw = *(const u32x4*)(H + o); r0 = (f32x4){bflo(hw.x), bfhi(hw.x), bflo(hw.y), bfhi(hw.y)}; r1 = (f32x4){bflo(hw.z), bfhi(hw.z), bflo(hw.w), bfhi(hw.w)}; }
;                         *(u32x4*)(H + o) = pack8(r0 + acc[ai][bj][m][0], r1 + acc[ai][bj][m][1]); } }
;                 asm volatile("" ::: "memory"); }
.Lp4_proc_h:
	s_add_u32 s8, s0, 0x0
	s_addc_u32 s9, s1, 0
	s_waitcnt vmcnt(15)
	v_lshlrev_b32_e32 v151, 16, v128
	v_and_b32_e32 v128, 0xffff0000, v128
	v_add_f32_e32 v124, v124, v151
	v_add_f32_e32 v125, v125, v128
	v_lshlrev_b32_e32 v151, 16, v129
	v_and_b32_e32 v129, 0xffff0000, v129
	v_add_f32_e32 v126, v126, v151
	v_add_f32_e32 v127, v127, v129
	v_lshlrev_b32_e32 v151, 16, v130
	v_and_b32_e32 v130, 0xffff0000, v130
	v_add_f32_e32 v120, v120, v151
	v_add_f32_e32 v121, v121, v130
	v_lshlrev_b32_e32 v151, 16, v131
	v_and_b32_e32 v131, 0xffff0000, v131
	v_add_f32_e32 v122, v122, v151
	v_add_f32_e32 v123, v123, v131
	v_cvt_pk_bf16_f32 v128, v124, v125
	v_cvt_pk_bf16_f32 v129, v126, v127
	v_cvt_pk_bf16_f32 v130, v120, v121
	v_cvt_pk_bf16_f32 v131, v122, v123
	global_store_dwordx4 v150, v[128:131], s[8:9]
	s_waitcnt vmcnt(15)
	v_lshlrev_b32_e32 v151, 16, v132
	v_and_b32_e32 v132, 0xffff0000, v132
	v_add_f32_e32 v116, v116, v151
	v_add_f32_e32 v117, v117, v132
	v_lshlrev_b32_e32 v151, 16, v133
	v_and_b32_e32 v133, 0xffff0000, v133
	v_add_f32_e32 v118, v118, v151
	v_add_f32_e32 v119, v119, v133
	v_lshlrev_b32_e32 v151, 16, v134
	v_and_b32_e32 v134, 0xffff0000, v134
	v_add_f32_e32 v112, v112, v151
	v_add_f32_e32 v113, v113, v134
	v_lshlrev_b32_e32 v151, 16, v135
	v_and_b32_e32 v135, 0xffff0000, v135
	v_add_f32_e32 v114, v114, v151
	v_add_f32_e32 v115, v115, v135
	v_cvt_pk_bf16_f32 v132, v116, v117
	v_cvt_pk_bf16_f32 v133, v118, v119
	v_cvt_pk_bf16_f32 v134, v112, v113
	v_cvt_pk_bf16_f32 v135, v114, v115
	global_store_dwordx4 v150, v[132:135], s[8:9] offset:256
	s_add_u32 s8, s0, 0x8000
	s_addc_u32 s9, s1, 0
	s_waitcnt vmcnt(15)
	v_lshlrev_b32_e32 v151, 16, v146
	v_and_b32_e32 v146, 0xffff0000, v146
	v_add_f32_e32 v108, v108, v151
	v_add_f32_e32 v109, v109, v146
	v_lshlrev_b32_e32 v151, 16, v147
	v_and_b32_e32 v147, 0xffff0000, v147
	v_add_f32_e32 v110, v110, v151
	v_add_f32_e32 v111, v111, v147
	v_lshlrev_b32_e32 v151, 16, v148
	v_and_b32_e32 v148, 0xffff0000, v148
	v_add_f32_e32 v104, v104, v151
	v_add_f32_e32 v105, v105, v148
	v_lshlrev_b32_e32 v151, 16, v149
	v_and_b32_e32 v149, 0xffff0000, v149
	v_add_f32_e32 v106, v106, v151
	v_add_f32_e32 v107, v107, v149
	v_cvt_pk_bf16_f32 v146, v108, v109
	v_cvt_pk_bf16_f32 v147, v110, v111
	v_cvt_pk_bf16_f32 v148, v104, v105
	v_cvt_pk_bf16_f32 v149, v106, v107
	global_store_dwordx4 v150, v[146:149], s[8:9]
	s_waitcnt vmcnt(15)
	v_lshlrev_b32_e32 v151, 16, v158
	v_and_b32_e32 v158, 0xffff0000, v158
	v_add_f32_e32 v100, v100, v151
	v_add_f32_e32 v101, v101, v158
	v_lshlrev_b32_e32 v151, 16, v159
	v_and_b32_e32 v159, 0xffff0000, v159
	v_add_f32_e32 v102, v102, v151
	v_add_f32_e32 v103, v103, v159
	v_lshlrev_b32_e32 v151, 16, v160
	v_and_b32_e32 v160, 0xffff0000, v160
	v_add_f32_e32 v96, v96, v151
	v_add_f32_e32 v97, v97, v160
	v_lshlrev_b32_e32 v151, 16, v161
	v_and_b32_e32 v161, 0xffff0000, v161
	v_add_f32_e32 v98, v98, v151
	v_add_f32_e32 v99, v99, v161
	v_cvt_pk_bf16_f32 v158, v100, v101
	v_cvt_pk_bf16_f32 v159, v102, v103
	v_cvt_pk_bf16_f32 v160, v96, v97
	v_cvt_pk_bf16_f32 v161, v98, v99
	global_store_dwordx4 v150, v[158:161], s[8:9] offset:256
	s_add_u32 s8, s0, 0x10000
	s_addc_u32 s9, s1, 0
	s_waitcnt vmcnt(15)
	v_lshlrev_b32_e32 v151, 16, v162
	v_and_b32_e32 v162, 0xffff0000, v162
	v_add_f32_e32 v92, v92, v151
	v_add_f32_e32 v93, v93, v162
	v_lshlrev_b32_e32 v151, 16, v163
	v_and_b32_e32 v163, 0xffff0000, v163
	v_add_f32_e32 v94, v94, v151
	v_add_f32_e32 v95, v95, v163
	v_lshlrev_b32_e32 v151, 16, v164
	v_and_b32_e32 v164, 0xffff0000, v164
	v_add_f32_e32 v88, v88, v151
	v_add_f32_e32 v89, v89, v164
	v_lshlrev_b32_e32 v151, 16, v165
	v_and_b32_e32 v165, 0xffff0000, v165
	v_add_f32_e32 v90, v90, v151
	v_add_f32_e32 v91, v91, v165
	v_cvt_pk_bf16_f32 v162, v92, v93
	v_cvt_pk_bf16_f32 v163, v94, v95
	v_cvt_pk_bf16_f32 v164, v88, v89
	v_cvt_pk_bf16_f32 v165, v90, v91
	global_store_dwordx4 v150, v[162:165], s[8:9]
	s_waitcnt vmcnt(15)
	v_lshlrev_b32_e32 v151, 16, v166
	v_and_b32_e32 v166, 0xffff0000, v166
	v_add_f32_e32 v84, v84, v151
	v_add_f32_e32 v85, v85, v166
	v_lshlrev_b32_e32 v151, 16, v167
	v_and_b32_e32 v167, 0xffff0000, v167
	v_add_f32_e32 v86, v86, v151
	v_add_f32_e32 v87, v87, v167
	v_lshlrev_b32_e32 v151, 16, v168
	v_and_b32_e32 v168, 0xffff0000, v168
	v_add_f32_e32 v80, v80, v151
	v_add_f32_e32 v81, v81, v168
	v_lshlrev_b32_e32 v151, 16, v169
	v_and_b32_e32 v169, 0xffff0000, v169
	v_add_f32_e32 v82, v82, v151
	v_add_f32_e32 v83, v83, v169
	v_cvt_pk_bf16_f32 v166, v84, v85
	v_cvt_pk_bf16_f32 v167, v86, v87
	v_cvt_pk_bf16_f32 v168, v80, v81
	v_cvt_pk_bf16_f32 v169, v82, v83
	global_store_dwordx4 v150, v[166:169], s[8:9] offset:256
	s_add_u32 s8, s0, 0x18000
	s_addc_u32 s9, s1, 0
	s_waitcnt vmcnt(15)
	v_lshlrev_b32_e32 v151, 16, v170
	v_and_b32_e32 v170, 0xffff0000, v170
	v_add_f32_e32 v76, v76, v151
	v_add_f32_e32 v77, v77, v170
	v_lshlrev_b32_e32 v151, 16, v171
	v_and_b32_e32 v171, 0xffff0000, v171
	v_add_f32_e32 v78, v78, v151
	v_add_f32_e32 v79, v79, v171
	v_lshlrev_b32_e32 v151, 16, v172
	v_and_b32_e32 v172, 0xffff0000, v172
	v_add_f32_e32 v72, v72, v151
	v_add_f32_e32 v73, v73, v172
	v_lshlrev_b32_e32 v151, 16, v173
	v_and_b32_e32 v173, 0xffff0000, v173
	v_add_f32_e32 v74, v74, v151
	v_add_f32_e32 v75, v75, v173
	v_cvt_pk_bf16_f32 v170, v76, v77
	v_cvt_pk_bf16_f32 v171, v78, v79
	v_cvt_pk_bf16_f32 v172, v72, v73
	v_cvt_pk_bf16_f32 v173, v74, v75
	global_store_dwordx4 v150, v[170:173], s[8:9]
	s_waitcnt vmcnt(15)
; __device__ __forceinline__ u32x4 pack8(const f32x4 a, const f32x4 b) { u32x4 w; w.x = cvt_pk_bf16(a[0], a[1]); w.y = cvt_pk_bf16(a[2], a[3]); w.z = cvt_pk_bf16(b[0], b[1]); w.w = cvt_pk_bf16(b[2], b[3]); return w; }
;     __device__ __forceinline__ void operator()(const f32x4 (&acc)[2][2][4][2], const Unit& u, int wr, int wc, int fr, int fq) const {
;     ...
;             for (int m = 0; m < 4; ++m) { const size_t ro = (size_t)(row0 + ai * HALF + m * 16) * 1024 + col0;
; #pragma unroll
;                 for (int bj = 0; bj < 2; ++bj) { const size_t o = ro + bj * HALF;
;                     if (part) *(u32x4*)(pbase + o) = pack8(acc[ai][bj][m][0], acc[ai][bj][m][1]);
;                     else { f32x4 r0, r1;
;                         if (X32) { r0 = *(const f32x4*)(X32 + o); r1 = *(const f32x4*)(X32 + o + 4); }
;                         else { const u32x4 hw = *(const u32x4*)(H + o); r0 = (f32x4){bflo(hw.x), bfhi(hw.x), bflo(hw.y), bfhi(hw.y)}; r1 = (f32x4){bflo(hw.z), bfhi(hw.z), bflo(hw.w), bfhi(hw.w)}; }
;                         *(u32x4*)(H + o) = pack8(r0 + acc[ai][bj][m][0], r1 + acc[ai][bj][m][1]); } }
;                 asm volatile("" ::: "memory"); }
	v_lshlrev_b32_e32 v151, 16, v174
	v_and_b32_e32 v174, 0xffff0000, v174
	v_add_f32_e32 v68, v68, v151
	v_add_f32_e32 v69, v69, v174
	v_lshlrev_b32_e32 v151, 16, v175
	v_and_b32_e32 v175, 0xffff0000, v175
	v_add_f32_e32 v70, v70, v151
	v_add_f32_e32 v71, v71, v175
	v_lshlrev_b32_e32 v151, 16, v176
	v_and_b32_e32 v176, 0xffff0000, v176
	v_add_f32_e32 v64, v64, v151
	v_add_f32_e32 v65, v65, v176
	v_lshlrev_b32_e32 v151, 16, v177
	v_and_b32_e32 v177, 0xffff0000, v177
	v_add_f32_e32 v66, v66, v151
	v_add_f32_e32 v67, v67, v177
	v_cvt_pk_bf16_f32 v174, v68, v69
	v_cvt_pk_bf16_f32 v175, v70, v71
	v_cvt_pk_bf16_f32 v176, v64, v65
	v_cvt_pk_bf16_f32 v177, v66, v67
	global_store_dwordx4 v150, v[174:177], s[8:9] offset:256
	s_add_u32 s8, s0, 0x40000
	s_addc_u32 s9, s1, 0
	s_waitcnt vmcnt(15)
	v_lshlrev_b32_e32 v151, 16, v178
	v_and_b32_e32 v178, 0xffff0000, v178
	v_add_f32_e32 v60, v60, v151
	v_add_f32_e32 v61, v61, v178
	v_lshlrev_b32_e32 v151, 16, v179
	v_and_b32_e32 v179, 0xffff0000, v179
	v_add_f32_e32 v62, v62, v151
	v_add_f32_e32 v63, v63, v179
	v_lshlrev_b32_e32 v151, 16, v180
	v_and_b32_e32 v180, 0xffff0000, v180
	v_add_f32_e32 v56, v56, v151
	v_add_f32_e32 v57, v57, v180
	v_lshlrev_b32_e32 v151, 16, v181
	v_and_b32_e32 v181, 0xffff0000, v181
	v_add_f32_e32 v58, v58, v151
	v_add_f32_e32 v59, v59, v181
	v_cvt_pk_bf16_f32 v178, v60, v61
	v_cvt_pk_bf16_f32 v179, v62, v63
	v_cvt_pk_bf16_f32 v180, v56, v57
	v_cvt_pk_bf16_f32 v181, v58, v59
	global_store_dwordx4 v150, v[178:181], s[8:9]
	s_waitcnt vmcnt(15)
	v_lshlrev_b32_e32 v151, 16, v182
	v_and_b32_e32 v182, 0xffff0000, v182
	v_add_f32_e32 v52, v52, v151
	v_add_f32_e32 v53, v53, v182
	v_lshlrev_b32_e32 v151, 16, v183
	v_and_b32_e32 v183, 0xffff0000, v183
	v_add_f32_e32 v54, v54, v151
	v_add_f32_e32 v55, v55, v183
	v_lshlrev_b32_e32 v151, 16, v184
	v_and_b32_e32 v184, 0xffff0000, v184
	v_add_f32_e32 v48, v48, v151
	v_add_f32_e32 v49, v49, v184
	v_lshlrev_b32_e32 v151, 16, v185
	v_and_b32_e32 v185, 0xffff0000, v185
	v_add_f32_e32 v50, v50, v151
	v_add_f32_e32 v51, v51, v185
	v_cvt_pk_bf16_f32 v182, v52, v53
	v_cvt_pk_bf16_f32 v183, v54, v55
	v_cvt_pk_bf16_f32 v184, v48, v49
	v_cvt_pk_bf16_f32 v185, v50, v51
	global_store_dwordx4 v150, v[182:185], s[8:9] offset:256
	s_add_u32 s8, s0, 0x48000
	s_addc_u32 s9, s1, 0
	s_waitcnt vmcnt(15)
	v_lshlrev_b32_e32 v151, 16, v194
	v_and_b32_e32 v194, 0xffff0000, v194
	v_add_f32_e32 v44, v44, v151
	v_add_f32_e32 v45, v45, v194
	v_lshlrev_b32_e32 v151, 16, v195
	v_and_b32_e32 v195, 0xffff0000, v195
	v_add_f32_e32 v46, v46, v151
	v_add_f32_e32 v47, v47, v195
	v_lshlrev_b32_e32 v151, 16, v196
	v_and_b32_e32 v196, 0xffff0000, v196
	v_add_f32_e32 v40, v40, v151
	v_add_f32_e32 v41, v41, v196
	v_lshlrev_b32_e32 v151, 16, v197
	v_and_b32_e32 v197, 0xffff0000, v197
	v_add_f32_e32 v42, v42, v151
	v_add_f32_e32 v43, v43, v197
	v_cvt_pk_bf16_f32 v194, v44, v45
	v_cvt_pk_bf16_f32 v195, v46, v47
	v_cvt_pk_bf16_f32 v196, v40, v41
	v_cvt_pk_bf16_f32 v197, v42, v43
	global_store_dwordx4 v150, v[194:197], s[8:9]
	s_waitcnt vmcnt(15)
	v_lshlrev_b32_e32 v151, 16, v198
	v_and_b32_e32 v198, 0xffff0000, v198
	v_add_f32_e32 v36, v36, v151
	v_add_f32_e32 v37, v37, v198
	v_lshlrev_b32_e32 v151, 16, v199
	v_and_b32_e32 v199, 0xffff0000, v199
	v_add_f32_e32 v38, v38, v151
	v_add_f32_e32 v39, v39, v199
	v_lshlrev_b32_e32 v151, 16, v200
	v_and_b32_e32 v200, 0xffff0000, v200
	v_add_f32_e32 v32, v32, v151
	v_add_f32_e32 v33, v33, v200
	v_lshlrev_b32_e32 v151, 16, v201
	v_and_b32_e32 v201, 0xffff0000, v201
	v_add_f32_e32 v34, v34, v151
	v_add_f32_e32 v35, v35, v201
	v_cvt_pk_bf16_f32 v198, v36, v37
	v_cvt_pk_bf16_f32 v199, v38, v39
	v_cvt_pk_bf16_f32 v200, v32, v33
	v_cvt_pk_bf16_f32 v201, v34, v35
	global_store_dwordx4 v150, v[198:201], s[8:9] offset:256
	s_add_u32 s8, s0, 0x50000
	s_addc_u32 s9, s1, 0
	s_waitcnt vmcnt(15)
	v_lshlrev_b32_e32 v151, 16, v202
	v_and_b32_e32 v202, 0xffff0000, v202
	v_add_f32_e32 v28, v28, v151
	v_add_f32_e32 v29, v29, v202
	v_lshlrev_b32_e32 v151, 16, v203
	v_and_b32_e32 v203, 0xffff0000, v203
	v_add_f32_e32 v30, v30, v151
	v_add_f32_e32 v31, v31, v203
	v_lshlrev_b32_e32 v151, 16, v204
	v_and_b32_e32 v204, 0xffff0000, v204
	v_add_f32_e32 v24, v24, v151
	v_add_f32_e32 v25, v25, v204
	v_lshlrev_b32_e32 v151, 16, v205
	v_and_b32_e32 v205, 0xffff0000, v205
	v_add_f32_e32 v26, v26, v151
	v_add_f32_e32 v27, v27, v205
	v_cvt_pk_bf16_f32 v202, v28, v29
	v_cvt_pk_bf16_f32 v203, v30, v31
	v_cvt_pk_bf16_f32 v204, v24, v25
	v_cvt_pk_bf16_f32 v205, v26, v27
	global_store_dwordx4 v150, v[202:205], s[8:9]
	s_waitcnt vmcnt(15)
	v_lshlrev_b32_e32 v151, 16, v210
	v_and_b32_e32 v210, 0xffff0000, v210
	v_add_f32_e32 v20, v20, v151
	v_add_f32_e32 v21, v21, v210
	v_lshlrev_b32_e32 v151, 16, v211
	v_and_b32_e32 v211, 0xffff0000, v211
	v_add_f32_e32 v22, v22, v151
	v_add_f32_e32 v23, v23, v211
	v_lshlrev_b32_e32 v151, 16, v212
	v_and_b32_e32 v212, 0xffff0000, v212
	v_add_f32_e32 v16, v16, v151
	v_add_f32_e32 v17, v17, v212
	v_lshlrev_b32_e32 v151, 16, v213
	v_and_b32_e32 v213, 0xffff0000, v213
	v_add_f32_e32 v18, v18, v151
	v_add_f32_e32 v19, v19, v213
	v_cvt_pk_bf16_f32 v210, v20, v21
	v_cvt_pk_bf16_f32 v211, v22, v23
	v_cvt_pk_bf16_f32 v212, v16, v17
	v_cvt_pk_bf16_f32 v213, v18, v19
	global_store_dwordx4 v150, v[210:213], s[8:9] offset:256
	s_add_u32 s8, s0, 0x58000
	s_addc_u32 s9, s1, 0
	s_waitcnt vmcnt(15)
	v_lshlrev_b32_e32 v151, 16, v214
	v_and_b32_e32 v214, 0xffff0000, v214
	v_add_f32_e32 v12, v12, v151
	v_add_f32_e32 v13, v13, v214
	v_lshlrev_b32_e32 v151, 16, v215
	v_and_b32_e32 v215, 0xffff0000, v215
	v_add_f32_e32 v14, v14, v151
	v_add_f32_e32 v15, v15, v215
	v_lshlrev_b32_e32 v151, 16, v216
	v_and_b32_e32 v216, 0xffff0000, v216
	v_add_f32_e32 v8, v8, v151
	v_add_f32_e32 v9, v9, v216
	v_lshlrev_b32_e32 v151, 16, v217
	v_and_b32_e32 v217, 0xffff0000, v217
	v_add_f32_e32 v10, v10, v151
	v_add_f32_e32 v11, v11, v217
	v_cvt_pk_bf16_f32 v214, v12, v13
	v_cvt_pk_bf16_f32 v215, v14, v15
	v_cvt_pk_bf16_f32 v216, v8, v9
	v_cvt_pk_bf16_f32 v217, v10, v11
	global_store_dwordx4 v150, v[214:217], s[8:9]
	s_waitcnt vmcnt(15)
	v_lshlrev_b32_e32 v151, 16, v218
	v_and_b32_e32 v218, 0xffff0000, v218
	v_add_f32_e32 v4, v4, v151
	v_add_f32_e32 v5, v5, v218
	v_lshlrev_b32_e32 v151, 16, v219
	v_and_b32_e32 v219, 0xffff0000, v219
	v_add_f32_e32 v6, v6, v151
	v_add_f32_e32 v7, v7, v219
	v_lshlrev_b32_e32 v151, 16, v220
	v_and_b32_e32 v220, 0xffff0000, v220
	v_add_f32_e32 v0, v0, v151
	v_add_f32_e32 v1, v1, v220
	v_lshlrev_b32_e32 v151, 16, v221
	v_and_b32_e32 v221, 0xffff0000, v221
	v_add_f32_e32 v2, v2, v151
	v_add_f32_e32 v3, v3, v221
	v_cvt_pk_bf16_f32 v218, v4, v5
	v_cvt_pk_bf16_f32 v219, v6, v7
	v_cvt_pk_bf16_f32 v220, v0, v1
	v_cvt_pk_bf16_f32 v221, v2, v3
	global_store_dwordx4 v150, v[218:221], s[8:9] offset:256
	s_branch .Lp4_done

; #define PG8_BAR __builtin_amdgcn_s_barrier()
; template <class Epi, class Sched, bool ALIGN_EPI = false, bool SP2 = false>
; __device__ __forceinline__ void gemm_phase(PG8_LAS unsigned char* lds, const Gemm g, const Sched& S, const Epi& E) {
;     ...
;         if constexpr (ALIGN_EPI) { if (wr == 0) PG8_BAR; }
;         if constexpr (!Epi::AFTER_DRAIN) { E(acc, cur, wr, wc, fr, fq); S.done(cur); }
;         if (!has_next) break;
; #pragma unroll
;         for (int a = 0; a < 2; ++a)
; #pragma unroll
;             for (int b = 0; b < 2; ++b)
; #pragma unroll
;                 for (int m = 0; m < 4; ++m)
; #pragma unroll
;                     for (int n = 0; n < 2; ++n) acc[a][b][m][n] = zero4_;
;         cur = nxt; cA = nA; cB = nB; ++ui;
;         if constexpr (ALIGN_EPI) { if (wr == 1) PG8_BAR; }
;     }
.Lp4_done:
	s_andn2_b64 vcc, exec, s[24:25]
	s_mov_b64 s[0:1], -1
	s_cbranch_vccnz .LBB0_868
	s_and_b64 s[0:1], s[6:7], exec
	s_cselect_b32 s9, 16, 4
	s_andn2_b64 vcc, exec, s[10:11]
	s_cbranch_vccnz .LBB0_867
	s_barrier
	s_branch .LBB0_867
